# GLA chain step: ot output stores merged to dwordx4 via v_permlane32_swap (8->4 stores per step, vmcnt recounted) and v_pk_mul_f32 decay scaling replaced by scalar v_mul_f32; plus earlier GEMM K-loop D
# speedup vs baseline: 1.0172x; 1.0121x over previous
; #define CH_LOAD_V(SET, st) do { const int gc_ = CH_GC(CH_CLAMP(st)); _Pragma("unroll") for (int ks = 0; ks < 4; ++ks) vf##SET[ks] = *(const bf16x8*)(vtg + ((size_t)(gc_ * 4 + h) * 256 + 32 * wave + l32) * 64 + 16 * ks + 8 * hh); } while (0)
; #define CH_STAGE(SET, buf) do { *(LAS u32x4*)((buf) + qt0 * 272 + qc0 * 16) = q0##SET; *(LAS u32x4*)((buf) + (qt0 + 32) * 272 + qc0 * 16) = q1##SET; \
;         *(LAS u32x4*)((buf) + CH_OFFK + kd0 * 144 + kc0 * 16) = k0##SET; *(LAS u32x4*)((buf) + CH_OFFK + (kd0 + 64) * 144 + kc0 * 16) = k1##SET; \
;         if (tid < 32) *(LAS f32x4*)((buf) + CH_OFFE + tid * 16) = en##SET; } while (0)
; __device__ __forceinline__ void gla_chain(LAS unsigned char* lds, int ci, int nchunk, bf16_t* proj, const bf16_t* kltf, const bf16_t* kltb, const bf16_t* vtg, const float* ef, const float* eb, bf16_t* ob, bf16_t* of2, unsigned* done, bf16_t* dry = nullptr) {
;     ...
;     f32x16 S[4];
; #pragma unroll
;     for (int i = 0; i < 4; ++i) S[i] = f32x16{};
;     ...
;     u32x4 q0A, q1A, k0A, k1A, q0B, q1B, k0B, k1B; f32x4 enA = (f32x4){0.f, 0.f, 0.f, 0.f}, enB = enA; bf16x8 vfA[4], vfB[4];
;     CH_LOAD_T(A, 0); CH_LOAD_V(A, 0);
;     CH_STAGE(A, lds);
;     CH_LOAD_T(B, 1); CH_LOAD_V(B, 1);
;     __syncthreads();
.LBB0_199:
	s_or_b64 exec, exec, s[0:1]
	s_lshl_b64 s[0:1], s[2:3], 8
	s_add_u32 s0, s0, s8
	s_addc_u32 s1, s1, s9
	v_mov_b32_e32 v7, s1
	v_or_b32_e32 v6, s0, v219
	v_readlane_b32 s2, v254, 40
	v_lshlrev_b32_e32 v4, 3, v25
	v_lshlrev_b64 v[6:7], 7, v[6:7]
	v_readlane_b32 s3, v254, 41
	v_lshlrev_b32_e32 v8, 1, v4
	v_mov_b32_e32 v9, v1
	v_lshl_add_u64 v[6:7], s[2:3], 0, v[6:7]
	v_lshl_add_u64 v[6:7], v[6:7], 0, v[8:9]
	global_load_dwordx4 v[150:153], v[6:7], off
	global_load_dwordx4 v[146:149], v[6:7], off offset:32
	global_load_dwordx4 v[142:145], v[6:7], off offset:64
	global_load_dwordx4 v[138:141], v[6:7], off offset:96
	s_add_u32 s0, s94, s66
	s_addc_u32 s1, s95, 0
	v_mov_b32_e32 v3, v1
	v_lshl_add_u64 v[200:201], s[0:1], 0, v[2:3]
	s_and_b64 s[0:1], s[4:5], exec
	v_lshl_add_u64 v[6:7], s[2:3], 0, v[8:9]
	s_cselect_b32 s0, s25, s85
	s_cselect_b32 s1, s89, s84
	s_lshl_b32 s2, s12, 9
	s_add_u32 s2, s1, s2
	s_addc_u32 s3, s0, 0
	s_lshl_b64 s[0:1], s[8:9], 1
	v_add_u32_e32 v10, 0, v4
	v_mov_b32_e32 v3, s9
	v_or_b32_e32 v2, s8, v219
	s_add_u32 s0, s2, s0
	v_add_u32_e32 v221, v10, v4
	s_addc_u32 s1, s3, s1
	v_mov_b32_e32 v5, v1
	v_or_b32_e32 v8, 32, v219
	v_lshlrev_b64 v[2:3], 7, v[2:3]
	v_mul_u32_u24_e32 v11, 0x90, v219
	v_mad_u32_u24 v12, v219, s30, 0
	v_lshl_add_u64 v[202:203], s[0:1], 0, v[4:5]
	v_lshrrev_b32_e32 v66, 5, v213
	v_mul_u32_u24_e32 v66, 24, v66
	v_mov_b32_e32 v67, 0
	v_lshl_add_u64 v[202:203], v[202:203], 0, v[66:67]
	v_lshlrev_b32_e32 v4, 4, v217
	v_mul_u32_u24_e32 v5, 0x110, v219
	v_mul_u32_u24_e32 v8, 0x90, v8
	v_lshl_add_u64 v[206:207], v[6:7], 0, v[2:3]
	v_mad_u32_u24 v222, v219, s30, v221
	v_mov_b32_e32 v2, 0
	s_mov_b32 s8, 3
	v_lshl_add_u64 v[204:205], v[18:19], 2, s[6:7]
	v_add_u32_e32 v223, 0xd400, v222
	v_add_u32_e32 v224, v10, v5
	v_add_u32_e32 v225, v221, v11
	v_add_u32_e32 v226, v12, v186
	v_add_u32_e32 v227, v221, v8
	v_add_u32_e32 v228, 0, v4
	s_mov_b32 s6, s52
	v_mov_b32_e32 v3, v2
	v_mov_b32_e32 v4, v2
	v_mov_b32_e32 v5, v2
	v_mov_b32_e32 v6, v2
	v_mov_b32_e32 v7, v2
	v_mov_b32_e32 v8, v2
	v_mov_b32_e32 v9, v2
	v_mov_b32_e32 v10, v2
	v_mov_b32_e32 v11, v2
	v_mov_b32_e32 v12, v2
	v_mov_b32_e32 v13, v2
	v_mov_b32_e32 v14, v2
	v_mov_b32_e32 v15, v2
	v_mov_b32_e32 v16, v2
	v_mov_b32_e32 v17, v2
	v_mov_b32_e32 v18, v2
	v_mov_b32_e32 v19, v2
	v_mov_b32_e32 v20, v2
	v_mov_b32_e32 v21, v2
	v_mov_b32_e32 v22, v2
	v_mov_b32_e32 v23, v2
	v_mov_b32_e32 v24, v2
	v_mov_b32_e32 v25, v2
	v_mov_b32_e32 v26, v2
	v_mov_b32_e32 v27, v2
	v_mov_b32_e32 v28, v2
	v_mov_b32_e32 v29, v2
	v_mov_b32_e32 v30, v2
	v_mov_b32_e32 v31, v2
	v_mov_b32_e32 v32, v2
	v_mov_b32_e32 v33, v2
	v_mov_b32_e32 v34, v2
	v_mov_b32_e32 v35, v2
	v_mov_b32_e32 v36, v2
	v_mov_b32_e32 v37, v2
	v_mov_b32_e32 v38, v2
	v_mov_b32_e32 v39, v2
	v_mov_b32_e32 v40, v2
	v_mov_b32_e32 v41, v2
	v_mov_b32_e32 v42, v2
	v_mov_b32_e32 v43, v2
	v_mov_b32_e32 v44, v2
	v_mov_b32_e32 v45, v2
	v_mov_b32_e32 v46, v2
	v_mov_b32_e32 v47, v2
	v_mov_b32_e32 v48, v2
	v_mov_b32_e32 v49, v2
	v_mov_b32_e32 v50, v2
	v_mov_b32_e32 v51, v2
	v_mov_b32_e32 v52, v2
	v_mov_b32_e32 v53, v2
	v_mov_b32_e32 v54, v2
	v_mov_b32_e32 v55, v2
	v_mov_b32_e32 v56, v2
	v_mov_b32_e32 v57, v2
	v_mov_b32_e32 v58, v2
	v_mov_b32_e32 v59, v2
	v_mov_b32_e32 v60, v2
	v_mov_b32_e32 v61, v2
	v_mov_b32_e32 v62, v2
	v_mov_b32_e32 v63, v2
	v_mov_b32_e32 v64, v2
	v_mov_b32_e32 v65, v2
	s_waitcnt lgkmcnt(0)
	s_barrier
	s_branch .LBB0_201

.LBB0_203:
	s_or_b64 exec, exec, s[2:3]
	v_add_u32_e32 v190, 0x2000, v224
	ds_read2_b64 v[66:69], v224 offset1:2
	ds_read2_b64 v[170:173], v224 offset0:4 offset1:6
	ds_read2_b64 v[70:73], v190 offset0:64 offset1:66
	ds_read2_b64 v[174:177], v190 offset0:68 offset1:70
	ds_read2_b64 v[178:181], v224 offset0:8 offset1:10
	ds_read2_b64 v[182:185], v190 offset0:72 offset1:74
	ds_read2_b64 v[234:237], v224 offset0:12 offset1:14
	ds_read2_b64 v[238:241], v190 offset0:76 offset1:78
	s_add_i32 s7, s8, -3
	s_and_b64 s[2:3], s[4:5], exec
	s_cselect_b32 s2, s7, s6
	s_add_i32 s2, s2, s37
	v_cvt_pk_bf16_f32 v74, v50, v51
	v_cvt_pk_bf16_f32 v75, v52, v53
	v_cvt_pk_bf16_f32 v76, v54, v55
	v_cvt_pk_bf16_f32 v77, v56, v57
	v_cvt_pk_bf16_f32 v242, v58, v59
	v_cvt_pk_bf16_f32 v243, v60, v61
	s_waitcnt lgkmcnt(7)
	v_mfma_f32_32x32x16_bf16 v[82:97], v[74:77], v[66:69], 0
	v_cvt_pk_bf16_f32 v244, v62, v63
	v_cvt_pk_bf16_f32 v245, v64, v65
	s_waitcnt lgkmcnt(5)
	v_mfma_f32_32x32x16_bf16 v[66:81], v[74:77], v[70:73], 0
	v_mfma_f32_32x32x16_bf16 v[82:97], v[242:245], v[170:173], v[82:97]
	s_waitcnt lgkmcnt(4)
	v_mfma_f32_32x32x16_bf16 v[66:81], v[242:245], v[174:177], v[66:81]
	ds_read2_b64 v[170:173], v224 offset0:16 offset1:18
	ds_read2_b64 v[174:177], v224 offset0:20 offset1:22
	ds_read2_b64 v[242:245], v190 offset0:80 offset1:82
	ds_read2_b64 v[246:249], v190 offset0:84 offset1:86
	v_cvt_pk_bf16_f32 v194, v34, v35
	v_cvt_pk_bf16_f32 v195, v36, v37
	v_cvt_pk_bf16_f32 v196, v38, v39
	v_cvt_pk_bf16_f32 v197, v40, v41
	s_waitcnt lgkmcnt(7)
	s_nop 0
	v_mfma_f32_32x32x16_bf16 v[82:97], v[194:197], v[178:181], v[82:97]
	v_cvt_pk_bf16_f32 v178, v42, v43
	v_cvt_pk_bf16_f32 v179, v44, v45
	v_cvt_pk_bf16_f32 v180, v46, v47
	v_cvt_pk_bf16_f32 v181, v48, v49
	s_waitcnt lgkmcnt(6)
	v_mfma_f32_32x32x16_bf16 v[66:81], v[194:197], v[182:185], v[66:81]
	s_waitcnt lgkmcnt(5)
	v_mfma_f32_32x32x16_bf16 v[82:97], v[178:181], v[234:237], v[82:97]
	s_waitcnt lgkmcnt(4)
	v_mfma_f32_32x32x16_bf16 v[66:81], v[178:181], v[238:241], v[66:81]
	ds_read2_b64 v[194:197], v224 offset0:24 offset1:26
	ds_read2_b64 v[234:237], v224 offset0:28 offset1:30
	ds_read2_b64 v[238:241], v190 offset0:88 offset1:90
	ds_read2_b64 v[190:193], v190 offset0:92 offset1:94
	v_cvt_pk_bf16_f32 v178, v18, v19
	v_cvt_pk_bf16_f32 v179, v20, v21
	v_cvt_pk_bf16_f32 v180, v22, v23
	v_cvt_pk_bf16_f32 v181, v24, v25
	s_waitcnt lgkmcnt(7)
	s_nop 0
	v_mfma_f32_32x32x16_bf16 v[82:97], v[178:181], v[170:173], v[82:97]
	v_cvt_pk_bf16_f32 v170, v26, v27
	v_cvt_pk_bf16_f32 v171, v28, v29
	v_cvt_pk_bf16_f32 v172, v30, v31
	v_cvt_pk_bf16_f32 v173, v32, v33
	s_waitcnt lgkmcnt(5)
	v_mfma_f32_32x32x16_bf16 v[66:81], v[178:181], v[242:245], v[66:81]
	v_mfma_f32_32x32x16_bf16 v[82:97], v[170:173], v[174:177], v[82:97]
	s_waitcnt lgkmcnt(4)
	v_mfma_f32_32x32x16_bf16 v[66:81], v[170:173], v[246:249], v[66:81]
	ds_read_b128 v[182:185], v226 offset:17408
	ds_read_b128 v[178:181], v226 offset:17440
	ds_read_b128 v[174:177], v226 offset:17472
	ds_read_b128 v[170:173], v226 offset:17504
	v_cvt_pk_bf16_f32 v242, v2, v3
	v_cvt_pk_bf16_f32 v243, v4, v5
	v_cvt_pk_bf16_f32 v244, v6, v7
	v_cvt_pk_bf16_f32 v245, v8, v9
	s_waitcnt lgkmcnt(7)
	s_nop 0
	v_mfma_f32_32x32x16_bf16 v[82:97], v[242:245], v[194:197], v[82:97]
	v_cvt_pk_bf16_f32 v194, v10, v11
	v_cvt_pk_bf16_f32 v195, v12, v13
	v_cvt_pk_bf16_f32 v196, v14, v15
	v_cvt_pk_bf16_f32 v197, v16, v17
	s_waitcnt lgkmcnt(5)
	v_mfma_f32_32x32x16_bf16 v[66:81], v[242:245], v[238:241], v[66:81]
	v_mfma_f32_32x32x16_bf16 v[82:97], v[194:197], v[234:237], v[82:97]
	s_waitcnt lgkmcnt(4)
	v_mfma_f32_32x32x16_bf16 v[66:81], v[194:197], v[190:193], v[66:81]
	ds_read_b128 v[190:193], v221 offset:35840
	ds_read_b128 v[194:197], v221 offset:35872
	ds_read_b128 v[234:237], v221 offset:35904
	ds_read_b128 v[238:241], v221 offset:35936
	s_waitcnt lgkmcnt(3)
	v_mul_f32_e32 v52, v52, v192
	v_mul_f32_e32 v53, v53, v193
	s_waitcnt lgkmcnt(2)
	v_mul_f32_e32 v56, v56, v196
	v_mul_f32_e32 v57, v57, v197
	s_waitcnt lgkmcnt(1)
	v_mul_f32_e32 v60, v60, v236
	v_mul_f32_e32 v61, v61, v237
	s_waitcnt lgkmcnt(0)
	v_mul_f32_e32 v64, v64, v240
	v_mul_f32_e32 v65, v65, v241
	v_mul_f32_e32 v62, v62, v238
	v_mul_f32_e32 v63, v63, v239
	v_mul_f32_e32 v58, v58, v234
	v_mul_f32_e32 v59, v59, v235
	v_mul_f32_e32 v54, v54, v194
	v_mul_f32_e32 v55, v55, v195
	v_mul_f32_e32 v50, v50, v190
	v_mul_f32_e32 v51, v51, v191
	ds_read_b128 v[190:193], v221 offset:35968
	ds_read_b128 v[194:197], v221 offset:36000
	ds_read_b128 v[234:237], v221 offset:36032
	ds_read_b128 v[238:241], v221 offset:36064
	s_waitcnt lgkmcnt(3)
	v_mul_f32_e32 v36, v36, v192
	v_mul_f32_e32 v37, v37, v193
	s_waitcnt lgkmcnt(2)
	v_mul_f32_e32 v40, v40, v196
	v_mul_f32_e32 v41, v41, v197
	s_waitcnt lgkmcnt(1)
	v_mul_f32_e32 v44, v44, v236
	v_mul_f32_e32 v45, v45, v237
	s_waitcnt lgkmcnt(0)
	v_mul_f32_e32 v48, v48, v240
	v_mul_f32_e32 v49, v49, v241
	v_mul_f32_e32 v46, v46, v238
	v_mul_f32_e32 v47, v47, v239
	v_mul_f32_e32 v42, v42, v234
	v_mul_f32_e32 v43, v43, v235
	v_mul_f32_e32 v38, v38, v194
	v_mul_f32_e32 v39, v39, v195
	v_mul_f32_e32 v34, v34, v190
	v_mul_f32_e32 v35, v35, v191
	ds_read_b128 v[190:193], v221 offset:36096
	ds_read_b128 v[194:197], v221 offset:36128
	ds_read_b128 v[234:237], v221 offset:36160
	ds_read_b128 v[238:241], v221 offset:36192
	s_waitcnt lgkmcnt(3)
	v_mul_f32_e32 v20, v20, v192
	v_mul_f32_e32 v21, v21, v193
	s_waitcnt lgkmcnt(2)
	v_mul_f32_e32 v24, v24, v196
	v_mul_f32_e32 v25, v25, v197
	s_waitcnt lgkmcnt(1)
	v_mul_f32_e32 v28, v28, v236
	v_mul_f32_e32 v29, v29, v237
	s_waitcnt lgkmcnt(0)
	v_mul_f32_e32 v32, v32, v240
	v_mul_f32_e32 v33, v33, v241
	v_mul_f32_e32 v30, v30, v238
	v_mul_f32_e32 v31, v31, v239
	v_mul_f32_e32 v26, v26, v234
	v_mul_f32_e32 v27, v27, v235
	v_mul_f32_e32 v22, v22, v194
	v_mul_f32_e32 v23, v23, v195
	v_mul_f32_e32 v18, v18, v190
	v_mul_f32_e32 v19, v19, v191
	ds_read_b128 v[190:193], v221 offset:36224
	ds_read_b128 v[194:197], v221 offset:36256
	ds_read_b128 v[234:237], v221 offset:36288
	ds_read_b128 v[238:241], v221 offset:36320
	s_waitcnt lgkmcnt(3)
	v_mul_f32_e32 v4, v4, v192
	v_mul_f32_e32 v5, v5, v193
	s_waitcnt lgkmcnt(2)
	v_mul_f32_e32 v8, v8, v196
	v_mul_f32_e32 v9, v9, v197
	s_waitcnt lgkmcnt(1)
	v_mul_f32_e32 v12, v12, v236
	v_mul_f32_e32 v13, v13, v237
	s_waitcnt lgkmcnt(0)
	v_mul_f32_e32 v16, v16, v240
	v_mul_f32_e32 v17, v17, v241
	v_mul_f32_e32 v14, v14, v238
	v_mul_f32_e32 v15, v15, v239
	v_mul_f32_e32 v10, v10, v234
	v_mul_f32_e32 v11, v11, v235
	v_mul_f32_e32 v6, v6, v194
	v_mul_f32_e32 v7, v7, v195
	v_mul_f32_e32 v2, v2, v190
	v_mul_f32_e32 v3, v3, v191
	ds_read_b128 v[190:193], v227 offset:17408
	ds_read_b128 v[194:197], v227 offset:17440
	ds_read_b128 v[234:237], v227 offset:17472
	ds_read_b128 v[238:241], v227 offset:17504
	s_waitcnt vmcnt(15)
	v_mfma_f32_32x32x16_bf16 v[50:65], v[182:185], v[114:117], v[50:65]
	s_waitcnt vmcnt(14)
	v_mfma_f32_32x32x16_bf16 v[50:65], v[178:181], v[110:113], v[50:65]
	s_waitcnt vmcnt(13)
	v_mfma_f32_32x32x16_bf16 v[50:65], v[174:177], v[106:109], v[50:65]
	s_waitcnt vmcnt(12)
	v_mfma_f32_32x32x16_bf16 v[50:65], v[170:173], v[102:105], v[50:65]
	ds_read_b128 v[170:173], v225 offset:26624
	ds_read_b128 v[174:177], v225 offset:26656
	ds_read_b128 v[178:181], v225 offset:26688
	ds_read_b128 v[182:185], v225 offset:26720
	s_waitcnt lgkmcnt(7)
	v_mfma_f32_32x32x16_bf16 v[34:49], v[190:193], v[114:117], v[34:49]
	s_waitcnt lgkmcnt(6)
	v_mfma_f32_32x32x16_bf16 v[34:49], v[194:197], v[110:113], v[34:49]
	s_waitcnt lgkmcnt(5)
	v_mfma_f32_32x32x16_bf16 v[34:49], v[234:237], v[106:109], v[34:49]
	s_waitcnt lgkmcnt(4)
	v_mfma_f32_32x32x16_bf16 v[34:49], v[238:241], v[102:105], v[34:49]
	ds_read_b128 v[190:193], v225 offset:31232
	ds_read_b128 v[194:197], v225 offset:31264
	ds_read_b128 v[234:237], v225 offset:31296
	ds_read_b128 v[238:241], v225 offset:31328
	s_waitcnt lgkmcnt(7)
	v_mfma_f32_32x32x16_bf16 v[18:33], v[170:173], v[114:117], v[18:33]
	s_waitcnt lgkmcnt(6)
	v_mfma_f32_32x32x16_bf16 v[18:33], v[174:177], v[110:113], v[18:33]
	s_waitcnt lgkmcnt(5)
	v_mfma_f32_32x32x16_bf16 v[18:33], v[178:181], v[106:109], v[18:33]
	s_waitcnt lgkmcnt(4)
	v_mfma_f32_32x32x16_bf16 v[18:33], v[182:185], v[102:105], v[18:33]
	s_waitcnt lgkmcnt(3)
	v_mfma_f32_32x32x16_bf16 v[2:17], v[190:193], v[114:117], v[2:17]
	s_waitcnt lgkmcnt(2)
	v_mfma_f32_32x32x16_bf16 v[2:17], v[194:197], v[110:113], v[2:17]
	s_waitcnt lgkmcnt(1)
	v_mfma_f32_32x32x16_bf16 v[2:17], v[234:237], v[106:109], v[2:17]
	s_waitcnt lgkmcnt(0)
	v_mfma_f32_32x32x16_bf16 v[2:17], v[238:241], v[102:105], v[2:17]
	s_lshl_b64 s[0:1], s[0:1], 15
	v_lshl_add_u64 v[102:103], v[206:207], 0, s[0:1]
	global_load_dwordx4 v[114:117], v[102:103], off
	global_load_dwordx4 v[110:113], v[102:103], off offset:32
	global_load_dwordx4 v[106:109], v[102:103], off offset:64
	s_nop 0
	global_load_dwordx4 v[102:105], v[102:103], off offset:96
	v_lshl_or_b32 v170, s2, 6, v219
	v_ashrrev_i32_e32 v171, 31, v170
	v_lshlrev_b64 v[172:173], 11, v[170:171]
	v_lshl_add_u64 v[172:173], v[202:203], 0, v[172:173]
	v_cvt_pk_bf16_f32 v82, v82, v83
	v_cvt_pk_bf16_f32 v83, v84, v85
	v_cvt_pk_bf16_f32 v84, v90, v91
	v_cvt_pk_bf16_f32 v85, v92, v93
	v_cvt_pk_bf16_f32 v86, v86, v87
	v_cvt_pk_bf16_f32 v87, v88, v89
	v_cvt_pk_bf16_f32 v88, v94, v95
	v_cvt_pk_bf16_f32 v89, v96, v97
	v_or_b32_e32 v90, 32, v170
	v_ashrrev_i32_e32 v91, 31, v90
	v_permlane32_swap_b32_e32 v82, v84
	v_permlane32_swap_b32_e32 v83, v85
	v_permlane32_swap_b32_e32 v86, v88
	v_permlane32_swap_b32_e32 v87, v89
	global_store_dwordx4 v[172:173], v[82:85], off
	global_store_dwordx4 v[172:173], v[86:89], off offset:16
	v_lshlrev_b64 v[90:91], 11, v[90:91]
	v_lshl_add_u64 v[90:91], v[202:203], 0, v[90:91]
	v_cvt_pk_bf16_f32 v66, v66, v67
	v_cvt_pk_bf16_f32 v67, v68, v69
	v_cvt_pk_bf16_f32 v68, v74, v75
	v_cvt_pk_bf16_f32 v69, v76, v77
	v_cvt_pk_bf16_f32 v70, v70, v71
	v_cvt_pk_bf16_f32 v71, v72, v73
	v_cvt_pk_bf16_f32 v72, v78, v79
	v_cvt_pk_bf16_f32 v73, v80, v81
	s_nop 1
	v_permlane32_swap_b32_e32 v66, v68
	v_permlane32_swap_b32_e32 v67, v69
	v_permlane32_swap_b32_e32 v70, v72
	v_permlane32_swap_b32_e32 v71, v73
	global_store_dwordx4 v[90:91], v[66:69], off
	global_store_dwordx4 v[90:91], v[70:73], off offset:16
	s_waitcnt vmcnt(19)
	ds_write_b128 v187, v[118:121] offset:36864
	s_waitcnt vmcnt(18)
	ds_write_b128 v187, v[122:125] offset:45568
	s_waitcnt vmcnt(17)
	ds_write_b128 v220, v[130:133] offset:54272
	s_waitcnt vmcnt(16)
	ds_write_b128 v220, v[134:137] offset:63488
	s_and_saveexec_b64 s[0:1], vcc
	v_add_u32_e32 v66, 0x11c00, v228
	ds_write_b128 v66, v[126:129]
	s_or_b64 exec, exec, s[0:1]
	v_mov_b32_e32 v66, s8
	s_min_u32 s2, s8, s52
	v_sub_u32_e64 v66, s52, v66 clamp
	s_and_b64 s[0:1], s[4:5], exec
	v_readfirstlane_b32 s0, v66
	s_cselect_b32 s0, s2, s0
	s_add_i32 s2, s0, s37
	v_lshl_add_u32 v68, s2, 6, v218
	v_mad_i64_i32 v[66:67], s[0:1], v68, s28, v[200:201]
	v_add_u32_e32 v68, 32, v68
	v_mad_i64_i32 v[68:69], s[0:1], v68, s28, v[200:201]
	s_lshl_b32 s0, s2, 2
	s_or_b32 s0, s0, s12
	s_ashr_i32 s1, s0, 31
	s_lshl_b64 s[2:3], s[0:1], 14
	s_add_u32 s2, s36, s2
	s_addc_u32 s3, s13, s3
	s_waitcnt lgkmcnt(0)
	s_barrier
	global_load_dwordx4 v[118:121], v[66:67], off
	global_load_dwordx4 v[122:125], v[68:69], off
	v_lshl_add_u64 v[66:67], v[188:189], 1, s[2:3]
	v_lshl_add_u64 v[66:67], v[66:67], 0, v[0:1]
	v_lshl_add_u64 v[68:69], v[198:199], 1, s[2:3]
	v_lshl_add_u64 v[68:69], v[68:69], 0, v[0:1]
	global_load_dwordx4 v[130:133], v[66:67], off
	global_load_dwordx4 v[134:137], v[68:69], off
	s_and_saveexec_b64 s[2:3], vcc
	s_cbranch_execz .LBB0_207
	s_lshl_b64 s[14:15], s[0:1], 9
	v_lshl_add_u64 v[66:67], v[204:205], 0, s[14:15]
	global_load_dwordx4 v[126:129], v[66:67], off
.LBB0_207:
	s_or_b64 exec, exec, s[2:3]
	v_add_u32_e32 v229, 0x9000, v224
	v_add_u32_e32 v246, 0xb000, v224
	ds_read2_b64 v[66:69], v229 offset1:2
	ds_read2_b64 v[170:173], v229 offset0:4 offset1:6
	ds_read2_b64 v[70:73], v246 offset0:64 offset1:66
	ds_read2_b64 v[174:177], v246 offset0:68 offset1:70
	ds_read2_b64 v[178:181], v229 offset0:8 offset1:10
	ds_read2_b64 v[182:185], v246 offset0:72 offset1:74
	ds_read2_b64 v[190:193], v229 offset0:12 offset1:14
	ds_read2_b64 v[194:197], v246 offset0:76 offset1:78
	s_xor_b32 s2, s7, 0x3fffffe
	s_add_i32 s3, s2, s81
	s_add_i32 s2, s7, 1
	s_and_b64 s[14:15], s[4:5], exec
	s_cselect_b32 s3, s2, s3
	s_add_i32 s3, s3, s37
	v_cvt_pk_bf16_f32 v74, v50, v51
	v_cvt_pk_bf16_f32 v75, v52, v53
	v_cvt_pk_bf16_f32 v76, v54, v55
	v_cvt_pk_bf16_f32 v77, v56, v57
	v_cvt_pk_bf16_f32 v234, v58, v59
	v_cvt_pk_bf16_f32 v235, v60, v61
	s_waitcnt lgkmcnt(7)
	v_mfma_f32_32x32x16_bf16 v[82:97], v[74:77], v[66:69], 0
	v_cvt_pk_bf16_f32 v236, v62, v63
	v_cvt_pk_bf16_f32 v237, v64, v65
	s_waitcnt lgkmcnt(5)
	v_mfma_f32_32x32x16_bf16 v[66:81], v[74:77], v[70:73], 0
	v_mfma_f32_32x32x16_bf16 v[82:97], v[234:237], v[170:173], v[82:97]
	s_waitcnt lgkmcnt(4)
	v_mfma_f32_32x32x16_bf16 v[66:81], v[234:237], v[174:177], v[66:81]
	ds_read2_b64 v[170:173], v229 offset0:16 offset1:18
	ds_read2_b64 v[174:177], v229 offset0:20 offset1:22
	ds_read2_b64 v[234:237], v246 offset0:80 offset1:82
	ds_read2_b64 v[238:241], v246 offset0:84 offset1:86
	v_cvt_pk_bf16_f32 v242, v34, v35
	v_cvt_pk_bf16_f32 v243, v36, v37
	v_cvt_pk_bf16_f32 v244, v38, v39
	v_cvt_pk_bf16_f32 v245, v40, v41
	s_waitcnt lgkmcnt(7)
	s_nop 0
	v_mfma_f32_32x32x16_bf16 v[82:97], v[242:245], v[178:181], v[82:97]
	v_cvt_pk_bf16_f32 v178, v42, v43
	v_cvt_pk_bf16_f32 v179, v44, v45
	v_cvt_pk_bf16_f32 v180, v46, v47
	v_cvt_pk_bf16_f32 v181, v48, v49
	s_waitcnt lgkmcnt(6)
	v_mfma_f32_32x32x16_bf16 v[66:81], v[242:245], v[182:185], v[66:81]
	s_waitcnt lgkmcnt(5)
	v_mfma_f32_32x32x16_bf16 v[82:97], v[178:181], v[190:193], v[82:97]
	s_waitcnt lgkmcnt(4)
	v_mfma_f32_32x32x16_bf16 v[66:81], v[178:181], v[194:197], v[66:81]
	ds_read2_b64 v[190:193], v229 offset0:24 offset1:26
	ds_read2_b64 v[194:197], v229 offset0:28 offset1:30
	ds_read2_b64 v[242:245], v246 offset0:88 offset1:90
	ds_read2_b64 v[246:249], v246 offset0:92 offset1:94
	v_cvt_pk_bf16_f32 v178, v18, v19
	v_cvt_pk_bf16_f32 v179, v20, v21
	v_cvt_pk_bf16_f32 v180, v22, v23
	v_cvt_pk_bf16_f32 v181, v24, v25
	s_waitcnt lgkmcnt(7)
	s_nop 0
	v_mfma_f32_32x32x16_bf16 v[82:97], v[178:181], v[170:173], v[82:97]
	v_cvt_pk_bf16_f32 v170, v26, v27
	v_cvt_pk_bf16_f32 v171, v28, v29
	v_cvt_pk_bf16_f32 v172, v30, v31
	v_cvt_pk_bf16_f32 v173, v32, v33
	s_waitcnt lgkmcnt(5)
	v_mfma_f32_32x32x16_bf16 v[66:81], v[178:181], v[234:237], v[66:81]
	v_mfma_f32_32x32x16_bf16 v[82:97], v[170:173], v[174:177], v[82:97]
	s_waitcnt lgkmcnt(4)
	v_mfma_f32_32x32x16_bf16 v[66:81], v[170:173], v[238:241], v[66:81]
	ds_read_b128 v[182:185], v226 offset:54272
	ds_read_b128 v[178:181], v226 offset:54304
	ds_read_b128 v[174:177], v226 offset:54336
	ds_read_b128 v[170:173], v226 offset:54368
	v_cvt_pk_bf16_f32 v234, v2, v3
	v_cvt_pk_bf16_f32 v235, v4, v5
	v_cvt_pk_bf16_f32 v236, v6, v7
	v_cvt_pk_bf16_f32 v237, v8, v9
	s_waitcnt lgkmcnt(7)
	s_nop 0
	v_mfma_f32_32x32x16_bf16 v[82:97], v[234:237], v[190:193], v[82:97]
	v_cvt_pk_bf16_f32 v190, v10, v11
	v_cvt_pk_bf16_f32 v191, v12, v13
	v_cvt_pk_bf16_f32 v192, v14, v15
	v_cvt_pk_bf16_f32 v193, v16, v17
	s_waitcnt lgkmcnt(5)
	v_mfma_f32_32x32x16_bf16 v[66:81], v[234:237], v[242:245], v[66:81]
	v_mfma_f32_32x32x16_bf16 v[82:97], v[190:193], v[194:197], v[82:97]
	s_waitcnt lgkmcnt(4)
	v_mfma_f32_32x32x16_bf16 v[66:81], v[190:193], v[246:249], v[66:81]
	v_add_u32_e32 v190, 0, v186
	v_add_u32_e32 v229, 0x11c00, v190
	ds_read_b128 v[190:193], v229
	ds_read_b128 v[194:197], v229 offset:32
	ds_read_b128 v[234:237], v229 offset:64
	ds_read_b128 v[238:241], v229 offset:96
	s_waitcnt lgkmcnt(3)
	v_mul_f32_e32 v52, v52, v192
	v_mul_f32_e32 v53, v53, v193
	s_waitcnt lgkmcnt(2)
	v_mul_f32_e32 v54, v54, v194
	v_mul_f32_e32 v55, v55, v195
	s_waitcnt lgkmcnt(1)
	v_mul_f32_e32 v58, v58, v234
	v_mul_f32_e32 v59, v59, v235
	s_waitcnt lgkmcnt(0)
	v_mul_f32_e32 v62, v62, v238
	v_mul_f32_e32 v63, v63, v239
	v_mul_f32_e32 v64, v64, v240
	v_mul_f32_e32 v65, v65, v241
	v_mul_f32_e32 v60, v60, v236
	v_mul_f32_e32 v61, v61, v237
	v_mul_f32_e32 v56, v56, v196
	v_mul_f32_e32 v57, v57, v197
	v_mul_f32_e32 v50, v50, v190
	v_mul_f32_e32 v51, v51, v191
	ds_read_b128 v[190:193], v229 offset:128
	ds_read_b128 v[194:197], v229 offset:160
	ds_read_b128 v[234:237], v229 offset:192
	ds_read_b128 v[238:241], v229 offset:224
	s_waitcnt lgkmcnt(3)
	v_mul_f32_e32 v36, v36, v192
	v_mul_f32_e32 v37, v37, v193
	s_waitcnt lgkmcnt(2)
	v_mul_f32_e32 v38, v38, v194
	v_mul_f32_e32 v39, v39, v195
	s_waitcnt lgkmcnt(1)
	v_mul_f32_e32 v42, v42, v234
	v_mul_f32_e32 v43, v43, v235
	s_waitcnt lgkmcnt(0)
	v_mul_f32_e32 v46, v46, v238
	v_mul_f32_e32 v47, v47, v239
	v_mul_f32_e32 v48, v48, v240
	v_mul_f32_e32 v49, v49, v241
	v_mul_f32_e32 v44, v44, v236
	v_mul_f32_e32 v45, v45, v237
	v_mul_f32_e32 v40, v40, v196
	v_mul_f32_e32 v41, v41, v197
	v_mul_f32_e32 v34, v34, v190
	v_mul_f32_e32 v35, v35, v191
	ds_read_b128 v[190:193], v229 offset:256
	ds_read_b128 v[194:197], v229 offset:288
	ds_read_b128 v[234:237], v229 offset:320
	ds_read_b128 v[238:241], v229 offset:352
	s_waitcnt lgkmcnt(3)
	v_mul_f32_e32 v20, v20, v192
	v_mul_f32_e32 v21, v21, v193
	s_waitcnt lgkmcnt(2)
	v_mul_f32_e32 v22, v22, v194
	v_mul_f32_e32 v23, v23, v195
	s_waitcnt lgkmcnt(1)
	v_mul_f32_e32 v26, v26, v234
	v_mul_f32_e32 v27, v27, v235
	s_waitcnt lgkmcnt(0)
	v_mul_f32_e32 v30, v30, v238
	v_mul_f32_e32 v31, v31, v239
	v_mul_f32_e32 v32, v32, v240
	v_mul_f32_e32 v33, v33, v241
	v_mul_f32_e32 v28, v28, v236
	v_mul_f32_e32 v29, v29, v237
	v_mul_f32_e32 v24, v24, v196
	v_mul_f32_e32 v25, v25, v197
	v_mul_f32_e32 v18, v18, v190
	v_mul_f32_e32 v19, v19, v191
	ds_read_b128 v[190:193], v229 offset:384
	ds_read_b128 v[194:197], v229 offset:416
	ds_read_b128 v[234:237], v229 offset:448
	ds_read_b128 v[238:241], v229 offset:480
	s_waitcnt lgkmcnt(3)
	v_mul_f32_e32 v4, v4, v192
	v_mul_f32_e32 v5, v5, v193
	s_waitcnt lgkmcnt(2)
	v_mul_f32_e32 v6, v6, v194
	v_mul_f32_e32 v7, v7, v195
	s_waitcnt lgkmcnt(1)
	v_mul_f32_e32 v10, v10, v234
	v_mul_f32_e32 v11, v11, v235
	s_waitcnt lgkmcnt(0)
	v_mul_f32_e32 v14, v14, v238
	v_mul_f32_e32 v15, v15, v239
	v_mul_f32_e32 v16, v16, v240
	v_mul_f32_e32 v17, v17, v241
	v_mul_f32_e32 v12, v12, v236
	v_mul_f32_e32 v13, v13, v237
	v_mul_f32_e32 v8, v8, v196
	v_mul_f32_e32 v9, v9, v197
	v_mul_f32_e32 v2, v2, v190
	v_mul_f32_e32 v3, v3, v191
	ds_read_b128 v[190:193], v227 offset:54272
	ds_read_b128 v[194:197], v227 offset:54304
	ds_read_b128 v[234:237], v227 offset:54336
	ds_read_b128 v[238:241], v227 offset:54368
	s_waitcnt vmcnt(19)
	v_mfma_f32_32x32x16_bf16 v[50:65], v[182:185], v[150:153], v[50:65]
	s_waitcnt vmcnt(18)
	v_mfma_f32_32x32x16_bf16 v[50:65], v[178:181], v[146:149], v[50:65]
	s_waitcnt vmcnt(17)
	v_mfma_f32_32x32x16_bf16 v[50:65], v[174:177], v[142:145], v[50:65]
	s_waitcnt vmcnt(16)
	v_mfma_f32_32x32x16_bf16 v[50:65], v[170:173], v[138:141], v[50:65]
	ds_read_b128 v[170:173], v222 offset:63488
	ds_read_b128 v[174:177], v222 offset:63520
	ds_read_b128 v[178:181], v222 offset:63552
	ds_read_b128 v[182:185], v222 offset:63584
	s_waitcnt lgkmcnt(7)
	v_mfma_f32_32x32x16_bf16 v[34:49], v[190:193], v[150:153], v[34:49]
	s_waitcnt lgkmcnt(6)
	v_mfma_f32_32x32x16_bf16 v[34:49], v[194:197], v[146:149], v[34:49]
	s_waitcnt lgkmcnt(5)
	v_mfma_f32_32x32x16_bf16 v[34:49], v[234:237], v[142:145], v[34:49]
	s_waitcnt lgkmcnt(4)
	v_mfma_f32_32x32x16_bf16 v[34:49], v[238:241], v[138:141], v[34:49]
	ds_read_b128 v[190:193], v223 offset:13824
	ds_read_b128 v[194:197], v223 offset:13856
	ds_read_b128 v[234:237], v223 offset:13888
	ds_read_b128 v[238:241], v223 offset:13920
	s_waitcnt lgkmcnt(7)
	v_mfma_f32_32x32x16_bf16 v[18:33], v[170:173], v[150:153], v[18:33]
	s_waitcnt lgkmcnt(6)
	v_mfma_f32_32x32x16_bf16 v[18:33], v[174:177], v[146:149], v[18:33]
	s_waitcnt lgkmcnt(5)
	v_mfma_f32_32x32x16_bf16 v[18:33], v[178:181], v[142:145], v[18:33]
	s_waitcnt lgkmcnt(4)
	v_mfma_f32_32x32x16_bf16 v[18:33], v[182:185], v[138:141], v[18:33]
	s_waitcnt lgkmcnt(3)
	v_mfma_f32_32x32x16_bf16 v[2:17], v[190:193], v[150:153], v[2:17]
	s_waitcnt lgkmcnt(2)
	v_mfma_f32_32x32x16_bf16 v[2:17], v[194:197], v[146:149], v[2:17]
	s_waitcnt lgkmcnt(1)
	v_mfma_f32_32x32x16_bf16 v[2:17], v[234:237], v[142:145], v[2:17]
	s_waitcnt lgkmcnt(0)
	v_mfma_f32_32x32x16_bf16 v[2:17], v[238:241], v[138:141], v[2:17]
	s_lshl_b64 s[0:1], s[0:1], 15
	v_lshl_add_u64 v[138:139], v[206:207], 0, s[0:1]
	global_load_dwordx4 v[150:153], v[138:139], off
	global_load_dwordx4 v[146:149], v[138:139], off offset:32
	global_load_dwordx4 v[142:145], v[138:139], off offset:64
	s_nop 0
	global_load_dwordx4 v[138:141], v[138:139], off offset:96
	v_lshl_or_b32 v170, s3, 6, v219
	v_ashrrev_i32_e32 v171, 31, v170
	v_lshlrev_b64 v[172:173], 11, v[170:171]
	v_lshl_add_u64 v[172:173], v[202:203], 0, v[172:173]
	v_cvt_pk_bf16_f32 v82, v82, v83
	v_cvt_pk_bf16_f32 v83, v84, v85
	v_cvt_pk_bf16_f32 v84, v90, v91
	v_cvt_pk_bf16_f32 v85, v92, v93
	v_cvt_pk_bf16_f32 v86, v86, v87
	v_cvt_pk_bf16_f32 v87, v88, v89
	v_cvt_pk_bf16_f32 v88, v94, v95
	v_cvt_pk_bf16_f32 v89, v96, v97
	v_or_b32_e32 v90, 32, v170
	v_ashrrev_i32_e32 v91, 31, v90
	v_permlane32_swap_b32_e32 v82, v84
	v_permlane32_swap_b32_e32 v83, v85
	v_permlane32_swap_b32_e32 v86, v88
	v_permlane32_swap_b32_e32 v87, v89
	global_store_dwordx4 v[172:173], v[82:85], off
	global_store_dwordx4 v[172:173], v[86:89], off offset:16
	v_lshlrev_b64 v[90:91], 11, v[90:91]
	v_lshl_add_u64 v[90:91], v[202:203], 0, v[90:91]
	v_cvt_pk_bf16_f32 v66, v66, v67
	v_cvt_pk_bf16_f32 v67, v68, v69
	v_cvt_pk_bf16_f32 v68, v74, v75
	v_cvt_pk_bf16_f32 v69, v76, v77
	v_cvt_pk_bf16_f32 v70, v70, v71
	v_cvt_pk_bf16_f32 v71, v72, v73
	v_cvt_pk_bf16_f32 v72, v78, v79
	v_cvt_pk_bf16_f32 v73, v80, v81
	s_nop 1
	v_permlane32_swap_b32_e32 v66, v68
	v_permlane32_swap_b32_e32 v67, v69
	v_permlane32_swap_b32_e32 v70, v72
	v_permlane32_swap_b32_e32 v71, v73
	global_store_dwordx4 v[90:91], v[66:69], off
	global_store_dwordx4 v[90:91], v[70:73], off offset:16
	s_waitcnt vmcnt(23)
	ds_write_b128 v187, v[154:157]
	s_waitcnt vmcnt(22)
	ds_write_b128 v187, v[158:161] offset:8704
	s_waitcnt vmcnt(21)
	ds_write_b128 v220, v[162:165] offset:17408
	s_waitcnt vmcnt(20)
	ds_write_b128 v220, v[166:169] offset:26624
	s_and_saveexec_b64 s[0:1], vcc
	s_cbranch_execz .LBB0_200
	ds_write_b128 v228, v[98:101] offset:35840
	s_branch .LBB0_200
